# Prologue split: shared pre-pass normalizes only group-0 rows; group 1 normalizes its own rows after the global barrier (overlaps group 0 first GEMM)
# baseline (speedup 1.0000x reference)
; __device__ __forceinline__ unsigned cvt_pk_bf16(float lo, float hi) { unsigned r; asm volatile("v_cvt_pk_bf16_f32 %0, %1, %2" : "=v"(r) : "v"(lo), "v"(hi)); return r; }
; __device__ __forceinline__ void rows_prenorm(const float* __restrict__ x, bf16_t* __restrict__ XN, float* __restrict__ RN, int bi, int nb, int nrows) {
;     const int lane = threadIdx.x & 63, gw = bi * 8 + (threadIdx.x >> 6), nw = nb * 8;
;     for (int row = gw; row < nrows; row += 2 * nw) {
;         f32x4 v[2][4]; float ss[2] = {0.f, 0.f};
; #pragma unroll
;         for (int u = 0; u < 2; ++u) { const float* xp = x + (size_t)(row + u * nw) * DM + 4 * lane;
; #pragma unroll
;             for (int c = 0; c < 4; ++c) v[u][c] = *(const f32x4*)(xp + 256 * c); }
; #pragma unroll
;         for (int u = 0; u < 2; ++u) {
; #pragma unroll
;             for (int c = 0; c < 4; ++c) ss[u] += sq4(v[u][c]);
;             ss[u] = wave_sum(ss[u]); const float ms = ss[u] * (1.0f / DM) + EPS, ri = rsqrtf(ms);
;             if (lane == 0) RN[row + u * nw] = ms * ri;
;             bf16_t* op = XN + (size_t)(row + u * nw) * DM + 4 * lane;
; #pragma unroll
;             for (int c = 0; c < 4; ++c) { u32x2 w; w.x = cvt_pk_bf16(v[u][c][0] * ri, v[u][c][1] * ri); w.y = cvt_pk_bf16(v[u][c][2] * ri, v[u][c][3] * ri); *(u32x2*)(op + 256 * c) = w; } }
;     }
; __global__ void __launch_bounds__(512, 2) mk_fwd(Args a) {
;     ...
;       rows_prenorm(a.in[0], (bf16_t*)(ws + WS_XN), (float*)(ws + WS_RN), bx, G, T); }
.LBB0_29:
	s_or_b64 exec, exec, s[0:1]
	s_mov_b64 s[98:99], s[4:5]
	s_add_u32 s0, s90, 0x3800000
	s_addc_u32 s1, s91, 0
	v_writelane_b32 v245, s0, 16
	s_add_u32 s6, s90, 0x1f810000
	s_addc_u32 s7, s91, 0
	v_writelane_b32 v245, s1, 17
	s_mov_b32 s0, 0x8000
	v_cmp_gt_i32_e32 vcc, s0, v176
	v_mbcnt_lo_u32_b32 v188, -1, 0
	v_lshlrev_b32_e32 v152, 3, v165
	s_and_saveexec_b64 s[2:3], vcc
	s_cbranch_execz .LBB0_36
	v_lshlrev_b32_e32 v0, 4, v165
	v_mov_b32_e32 v1, 0
	s_waitcnt vmcnt(47)
	v_lshl_add_u64 v[32:33], s[4:5], 0, v[0:1]
	v_mbcnt_hi_u32_b32 v0, -1, v188
	v_and_b32_e32 v2, 64, v0
	v_add_u32_e32 v2, 64, v2
	v_xor_b32_e32 v3, 32, v0
	v_cmp_lt_i32_e32 vcc, v3, v2
	v_readlane_b32 s0, v245, 16
	v_mov_b32_e32 v153, v1
	v_cndmask_b32_e32 v3, v0, v3, vcc
	s_waitcnt vmcnt(40)
	v_lshlrev_b32_e32 v40, 2, v3
	v_xor_b32_e32 v3, 16, v0
	v_cmp_lt_i32_e32 vcc, v3, v2
	v_readlane_b32 s1, v245, 17
	s_mov_b64 s[4:5], 0
	v_cndmask_b32_e32 v3, v0, v3, vcc
	s_waitcnt vmcnt(39)
	v_lshlrev_b32_e32 v41, 2, v3
	v_xor_b32_e32 v3, 8, v0
	v_cmp_lt_i32_e32 vcc, v3, v2
	v_lshl_add_u64 v[34:35], s[0:1], 0, v[152:153]
	s_waitcnt vmcnt(33)
	v_mov_b32_e32 v46, 0x358637bd
	v_cndmask_b32_e32 v3, v0, v3, vcc
	v_lshlrev_b32_e32 v42, 2, v3
	v_xor_b32_e32 v3, 4, v0
	v_cmp_lt_i32_e32 vcc, v3, v2
	s_mov_b32 s8, 0x800000
	s_movk_i32 s9, 0x3fff
	v_cndmask_b32_e32 v3, v0, v3, vcc
	v_lshlrev_b32_e32 v43, 2, v3
	v_xor_b32_e32 v3, 2, v0
	v_cmp_lt_i32_e32 vcc, v3, v2
	v_mov_b32_e32 v38, v176
	s_nop 0
	v_cndmask_b32_e32 v3, v0, v3, vcc
	v_lshlrev_b32_e32 v44, 2, v3
	v_xor_b32_e32 v3, 1, v0
	v_cmp_lt_i32_e32 vcc, v3, v2
	s_nop 1
	v_cndmask_b32_e32 v0, v0, v3, vcc
	v_lshlrev_b32_e32 v45, 2, v0
	v_cmp_eq_u32_e32 vcc, 0, v165
	s_branch .LBB0_32

; __device__ __forceinline__ unsigned cvt_pk_bf16(float lo, float hi) { unsigned r; asm volatile("v_cvt_pk_bf16_f32 %0, %1, %2" : "=v"(r) : "v"(lo), "v"(hi)); return r; }
; __device__ __forceinline__ void rows_prenorm(const float* __restrict__ x, bf16_t* __restrict__ XN, float* __restrict__ RN, int bi, int nb, int nrows) {
;     const int lane = threadIdx.x & 63, gw = bi * 8 + (threadIdx.x >> 6), nw = nb * 8;
;     for (int row = gw; row < nrows; row += 2 * nw) {
;         f32x4 v[2][4]; float ss[2] = {0.f, 0.f};
; #pragma unroll
;         for (int u = 0; u < 2; ++u) { const float* xp = x + (size_t)(row + u * nw) * DM + 4 * lane;
; #pragma unroll
;             for (int c = 0; c < 4; ++c) v[u][c] = *(const f32x4*)(xp + 256 * c); }
; #pragma unroll
;         for (int u = 0; u < 2; ++u) {
; #pragma unroll
;             for (int c = 0; c < 4; ++c) ss[u] += sq4(v[u][c]);
;             ss[u] = wave_sum(ss[u]); const float ms = ss[u] * (1.0f / DM) + EPS, ri = rsqrtf(ms);
;             if (lane == 0) RN[row + u * nw] = ms * ri;
;             bf16_t* op = XN + (size_t)(row + u * nw) * DM + 4 * lane;
; #pragma unroll
;             for (int c = 0; c < 4; ++c) { u32x2 w; w.x = cvt_pk_bf16(v[u][c][0] * ri, v[u][c][1] * ri); w.y = cvt_pk_bf16(v[u][c][2] * ri, v[u][c][3] * ri); *(u32x2*)(op + 256 * c) = w; } }
; __global__ void __launch_bounds__(512, 2) mk_fwd(Args a) {
;     ...
;     if (((blockIdx.x >> 2) & 1) == 1) { GV(); int tl = 0;
.LBB0_88:
	s_or_b64 exec, exec, s[0:1]
	s_add_u32 s20, s90, 0xb00000
	s_addc_u32 s21, s91, 0
	s_add_u32 s8, s90, 0x1080000
	s_addc_u32 s9, s91, 0
	s_add_u32 s96, s90, 0x1f80000
	s_addc_u32 s97, s91, 0
	s_add_u32 s94, s90, 0x2180000
	s_addc_u32 s95, s91, 0
	s_add_u32 s72, s90, 0x2380000
	s_addc_u32 s73, s91, 0
	s_add_u32 s70, s90, 0x2580000
	s_addc_u32 s71, s91, 0
	s_add_u32 s68, s90, 0x3080000
	s_addc_u32 s69, s91, 0
	s_ashr_i32 s33, s33, 1
	s_and_b32 s2, s93, 4
	s_cmp_eq_u32 s2, 0
	s_cselect_b64 s[0:1], -1, 0
	s_cmp_lg_u32 s2, 0
	s_cselect_b64 s[64:65], -1, 0
	s_and_b64 vcc, exec, s[0:1]
	s_waitcnt lgkmcnt(0)
	s_barrier
	s_cbranch_vccnz .LBB0_188
	s_lshr_b32 s32, s93, 1
	s_and_b32 s32, s32, 0x1ffffffc
	s_and_b32 s61, s93, 3
	s_or_b32 s32, s32, s61
	s_lshl_b32 s32, s32, 3
	s_addk_i32 s32, 0x4000
	v_add_u32_e32 v92, s32, v177
	v_mov_b32_e32 v93, 0
	v_lshlrev_b32_e32 v0, 4, v165
	v_mov_b32_e32 v1, 0
	v_lshl_add_u64 v[88:89], s[98:99], 0, v[0:1]
	v_readlane_b32 s74, v245, 16
	v_readlane_b32 s75, v245, 17
	v_lshlrev_b32_e32 v0, 3, v165
	s_nop 1
	v_lshl_add_u64 v[90:91], s[74:75], 0, v[0:1]
	s_add_u32 s100, s90, 0x1f810000
	s_addc_u32 s101, s91, 0
	v_mbcnt_lo_u32_b32 v0, -1, 0
	v_mbcnt_hi_u32_b32 v0, -1, v0
	v_xor_b32_e32 v1, 32, v0
	v_lshlrev_b32_e32 v80, 2, v1
	v_xor_b32_e32 v1, 16, v0
	v_lshlrev_b32_e32 v81, 2, v1
	v_xor_b32_e32 v1, 8, v0
	v_lshlrev_b32_e32 v82, 2, v1
	v_xor_b32_e32 v1, 4, v0
	v_lshlrev_b32_e32 v83, 2, v1
	v_xor_b32_e32 v1, 2, v0
	v_lshlrev_b32_e32 v84, 2, v1
	v_xor_b32_e32 v1, 1, v0
	v_lshlrev_b32_e32 v85, 2, v1
	v_mov_b32_e32 v86, 0x358637bd
	s_movk_i32 s32, 4
.Lg1pn_loop:
	v_lshlrev_b64 v[94:95], 12, v[92:93]
	v_lshl_add_u64 v[94:95], v[88:89], 0, v[94:95]
	global_load_dwordx4 v[0:3], v[94:95], off
	global_load_dwordx4 v[4:7], v[94:95], off offset:1024
	global_load_dwordx4 v[8:11], v[94:95], off offset:2048
	global_load_dwordx4 v[12:15], v[94:95], off offset:3072
	v_add_u32_e32 v96, 0x400, v92
	v_mov_b32_e32 v97, 0
	v_lshlrev_b64 v[94:95], 12, v[96:97]
	v_lshl_add_u64 v[94:95], v[88:89], 0, v[94:95]
	global_load_dwordx4 v[16:19], v[94:95], off
	global_load_dwordx4 v[20:23], v[94:95], off offset:1024
	global_load_dwordx4 v[24:27], v[94:95], off offset:2048
	global_load_dwordx4 v[28:31], v[94:95], off offset:3072
	v_add_u32_e32 v96, 0x800, v92
	v_mov_b32_e32 v97, 0
	v_lshlrev_b64 v[94:95], 12, v[96:97]
	v_lshl_add_u64 v[94:95], v[88:89], 0, v[94:95]
	global_load_dwordx4 v[32:35], v[94:95], off
	global_load_dwordx4 v[36:39], v[94:95], off offset:1024
	global_load_dwordx4 v[40:43], v[94:95], off offset:2048
	global_load_dwordx4 v[44:47], v[94:95], off offset:3072
	v_add_u32_e32 v96, 0xc00, v92
	v_mov_b32_e32 v97, 0
	v_lshlrev_b64 v[94:95], 12, v[96:97]
	v_lshl_add_u64 v[94:95], v[88:89], 0, v[94:95]
	global_load_dwordx4 v[48:51], v[94:95], off
	global_load_dwordx4 v[52:55], v[94:95], off offset:1024
	global_load_dwordx4 v[56:59], v[94:95], off offset:2048
	global_load_dwordx4 v[60:63], v[94:95], off offset:3072
	s_waitcnt vmcnt(0)
	v_mul_f32_e32 v64, v1, v1
	v_mul_f32_e32 v65, v5, v5
	v_mul_f32_e32 v66, v9, v9
	v_mul_f32_e32 v67, v13, v13
	v_fmac_f32_e32 v64, v0, v0
	v_fmac_f32_e32 v65, v4, v4
	v_fmac_f32_e32 v66, v8, v8
	v_fmac_f32_e32 v67, v12, v12
	v_fmac_f32_e32 v64, v2, v2
	v_fmac_f32_e32 v65, v6, v6
	v_fmac_f32_e32 v66, v10, v10
	v_fmac_f32_e32 v67, v14, v14
	v_fmac_f32_e32 v64, v3, v3
	v_fmac_f32_e32 v65, v7, v7
	v_fmac_f32_e32 v66, v11, v11
	v_fmac_f32_e32 v67, v15, v15
	v_add_f32_e32 v68, v64, v65
	v_add_f32_e32 v68, v68, v66
	v_add_f32_e32 v68, v68, v67
	ds_bpermute_b32 v69, v80, v68
	s_waitcnt lgkmcnt(0)
	v_add_f32_e32 v68, v68, v69
	ds_bpermute_b32 v69, v81, v68
	s_waitcnt lgkmcnt(0)
	v_add_f32_e32 v68, v68, v69
	ds_bpermute_b32 v69, v82, v68
	s_waitcnt lgkmcnt(0)
	v_add_f32_e32 v68, v68, v69
	ds_bpermute_b32 v69, v83, v68
	s_waitcnt lgkmcnt(0)
	v_add_f32_e32 v68, v68, v69
	ds_bpermute_b32 v69, v84, v68
	s_waitcnt lgkmcnt(0)
	v_add_f32_e32 v68, v68, v69
	ds_bpermute_b32 v69, v85, v68
	s_waitcnt lgkmcnt(0)
	v_add_f32_e32 v68, v68, v69
	v_fmamk_f32 v69, v68, 0x3a800000, v86
	v_mul_f32_e32 v68, 0x4b800000, v69
	v_cmp_gt_f32_e32 vcc, 0x800000, v69
	s_nop 1
	v_cndmask_b32_e32 v68, v69, v68, vcc
	v_rsq_f32_e32 v68, v68
	s_nop 0
	v_mul_f32_e32 v70, 0x45800000, v68
	v_cndmask_b32_e32 v68, v68, v70, vcc
	v_mov_b32_e32 v96, v92
	v_mov_b32_e32 v97, 0
	v_mul_f32_e32 v69, v69, v68
	v_lshl_add_u64 v[98:99], v[96:97], 2, s[100:101]
	s_mov_b64 exec, 1
	global_store_dword v[98:99], v69, off
	s_mov_b64 exec, -1
	v_lshlrev_b64 v[98:99], 11, v[96:97]
	v_lshl_add_u64 v[98:99], v[90:91], 0, v[98:99]
	v_mul_f32_e32 v0, v0, v68
	v_mul_f32_e32 v1, v1, v68
	v_mul_f32_e32 v2, v2, v68
	v_mul_f32_e32 v3, v3, v68
	v_cvt_pk_bf16_f32 v0, v0, v1
	v_cvt_pk_bf16_f32 v1, v2, v3
	global_store_dwordx2 v[98:99], v[0:1], off
	v_mul_f32_e32 v4, v4, v68
	v_mul_f32_e32 v5, v5, v68
	v_mul_f32_e32 v6, v6, v68
	v_mul_f32_e32 v7, v7, v68
	v_cvt_pk_bf16_f32 v4, v4, v5
	v_cvt_pk_bf16_f32 v5, v6, v7
	global_store_dwordx2 v[98:99], v[4:5], off offset:512
	v_mul_f32_e32 v8, v8, v68
	v_mul_f32_e32 v9, v9, v68
	v_mul_f32_e32 v10, v10, v68
	v_mul_f32_e32 v11, v11, v68
	v_cvt_pk_bf16_f32 v8, v8, v9
	v_cvt_pk_bf16_f32 v9, v10, v11
	global_store_dwordx2 v[98:99], v[8:9], off offset:1024
	v_mul_f32_e32 v12, v12, v68
	v_mul_f32_e32 v13, v13, v68
	v_mul_f32_e32 v14, v14, v68
	v_mul_f32_e32 v15, v15, v68
	v_cvt_pk_bf16_f32 v12, v12, v13
	v_cvt_pk_bf16_f32 v13, v14, v15
	global_store_dwordx2 v[98:99], v[12:13], off offset:1536
	v_mul_f32_e32 v64, v17, v17
	v_mul_f32_e32 v65, v21, v21
	v_mul_f32_e32 v66, v25, v25
	v_mul_f32_e32 v67, v29, v29
	v_fmac_f32_e32 v64, v16, v16
	v_fmac_f32_e32 v65, v20, v20
	v_fmac_f32_e32 v66, v24, v24
	v_fmac_f32_e32 v67, v28, v28
	v_fmac_f32_e32 v64, v18, v18
	v_fmac_f32_e32 v65, v22, v22
	v_fmac_f32_e32 v66, v26, v26
	v_fmac_f32_e32 v67, v30, v30
	v_fmac_f32_e32 v64, v19, v19
	v_fmac_f32_e32 v65, v23, v23
	v_fmac_f32_e32 v66, v27, v27
	v_fmac_f32_e32 v67, v31, v31
	v_add_f32_e32 v68, v64, v65
	v_add_f32_e32 v68, v68, v66
	v_add_f32_e32 v68, v68, v67
	ds_bpermute_b32 v69, v80, v68
	s_waitcnt lgkmcnt(0)
; __device__ __forceinline__ unsigned cvt_pk_bf16(float lo, float hi) { unsigned r; asm volatile("v_cvt_pk_bf16_f32 %0, %1, %2" : "=v"(r) : "v"(lo), "v"(hi)); return r; }
; __device__ __forceinline__ void rows_prenorm(const float* __restrict__ x, bf16_t* __restrict__ XN, float* __restrict__ RN, int bi, int nb, int nrows) {
;     ...
;         for (int u = 0; u < 2; ++u) { const float* xp = x + (size_t)(row + u * nw) * DM + 4 * lane;
; #pragma unroll
;             for (int c = 0; c < 4; ++c) v[u][c] = *(const f32x4*)(xp + 256 * c); }
; #pragma unroll
;         for (int u = 0; u < 2; ++u) {
; #pragma unroll
;             for (int c = 0; c < 4; ++c) ss[u] += sq4(v[u][c]);
;             ss[u] = wave_sum(ss[u]); const float ms = ss[u] * (1.0f / DM) + EPS, ri = rsqrtf(ms);
;             if (lane == 0) RN[row + u * nw] = ms * ri;
;             bf16_t* op = XN + (size_t)(row + u * nw) * DM + 4 * lane;
; #pragma unroll
;             for (int c = 0; c < 4; ++c) { u32x2 w; w.x = cvt_pk_bf16(v[u][c][0] * ri, v[u][c][1] * ri); w.y = cvt_pk_bf16(v[u][c][2] * ri, v[u][c][3] * ri); *(u32x2*)(op + 256 * c) = w; } }
	v_add_f32_e32 v68, v68, v69
	ds_bpermute_b32 v69, v81, v68
	s_waitcnt lgkmcnt(0)
	v_add_f32_e32 v68, v68, v69
	ds_bpermute_b32 v69, v82, v68
	s_waitcnt lgkmcnt(0)
	v_add_f32_e32 v68, v68, v69
	ds_bpermute_b32 v69, v83, v68
	s_waitcnt lgkmcnt(0)
	v_add_f32_e32 v68, v68, v69
	ds_bpermute_b32 v69, v84, v68
	s_waitcnt lgkmcnt(0)
	v_add_f32_e32 v68, v68, v69
	ds_bpermute_b32 v69, v85, v68
	s_waitcnt lgkmcnt(0)
	v_add_f32_e32 v68, v68, v69
	v_fmamk_f32 v69, v68, 0x3a800000, v86
	v_mul_f32_e32 v68, 0x4b800000, v69
	v_cmp_gt_f32_e32 vcc, 0x800000, v69
	s_nop 1
	v_cndmask_b32_e32 v68, v69, v68, vcc
	v_rsq_f32_e32 v68, v68
	s_nop 0
	v_mul_f32_e32 v70, 0x45800000, v68
	v_cndmask_b32_e32 v68, v68, v70, vcc
	v_add_u32_e32 v96, 0x400, v92
	v_mov_b32_e32 v97, 0
	v_mul_f32_e32 v69, v69, v68
	v_lshl_add_u64 v[98:99], v[96:97], 2, s[100:101]
	s_mov_b64 exec, 1
	global_store_dword v[98:99], v69, off
	s_mov_b64 exec, -1
	v_lshlrev_b64 v[98:99], 11, v[96:97]
	v_lshl_add_u64 v[98:99], v[90:91], 0, v[98:99]
	v_mul_f32_e32 v16, v16, v68
	v_mul_f32_e32 v17, v17, v68
	v_mul_f32_e32 v18, v18, v68
	v_mul_f32_e32 v19, v19, v68
	v_cvt_pk_bf16_f32 v16, v16, v17
	v_cvt_pk_bf16_f32 v17, v18, v19
	global_store_dwordx2 v[98:99], v[16:17], off
	v_mul_f32_e32 v20, v20, v68
	v_mul_f32_e32 v21, v21, v68
	v_mul_f32_e32 v22, v22, v68
	v_mul_f32_e32 v23, v23, v68
	v_cvt_pk_bf16_f32 v20, v20, v21
	v_cvt_pk_bf16_f32 v21, v22, v23
	global_store_dwordx2 v[98:99], v[20:21], off offset:512
	v_mul_f32_e32 v24, v24, v68
	v_mul_f32_e32 v25, v25, v68
	v_mul_f32_e32 v26, v26, v68
	v_mul_f32_e32 v27, v27, v68
	v_cvt_pk_bf16_f32 v24, v24, v25
	v_cvt_pk_bf16_f32 v25, v26, v27
	global_store_dwordx2 v[98:99], v[24:25], off offset:1024
	v_mul_f32_e32 v28, v28, v68
	v_mul_f32_e32 v29, v29, v68
	v_mul_f32_e32 v30, v30, v68
	v_mul_f32_e32 v31, v31, v68
	v_cvt_pk_bf16_f32 v28, v28, v29
	v_cvt_pk_bf16_f32 v29, v30, v31
	global_store_dwordx2 v[98:99], v[28:29], off offset:1536
	v_mul_f32_e32 v64, v33, v33
	v_mul_f32_e32 v65, v37, v37
	v_mul_f32_e32 v66, v41, v41
	v_mul_f32_e32 v67, v45, v45
	v_fmac_f32_e32 v64, v32, v32
	v_fmac_f32_e32 v65, v36, v36
	v_fmac_f32_e32 v66, v40, v40
	v_fmac_f32_e32 v67, v44, v44
	v_fmac_f32_e32 v64, v34, v34
	v_fmac_f32_e32 v65, v38, v38
	v_fmac_f32_e32 v66, v42, v42
	v_fmac_f32_e32 v67, v46, v46
	v_fmac_f32_e32 v64, v35, v35
	v_fmac_f32_e32 v65, v39, v39
	v_fmac_f32_e32 v66, v43, v43
	v_fmac_f32_e32 v67, v47, v47
	v_add_f32_e32 v68, v64, v65
	v_add_f32_e32 v68, v68, v66
	v_add_f32_e32 v68, v68, v67
	ds_bpermute_b32 v69, v80, v68
	s_waitcnt lgkmcnt(0)
	v_add_f32_e32 v68, v68, v69
	ds_bpermute_b32 v69, v81, v68
	s_waitcnt lgkmcnt(0)
	v_add_f32_e32 v68, v68, v69
	ds_bpermute_b32 v69, v82, v68
	s_waitcnt lgkmcnt(0)
	v_add_f32_e32 v68, v68, v69
	ds_bpermute_b32 v69, v83, v68
	s_waitcnt lgkmcnt(0)
	v_add_f32_e32 v68, v68, v69
	ds_bpermute_b32 v69, v84, v68
	s_waitcnt lgkmcnt(0)
	v_add_f32_e32 v68, v68, v69
	ds_bpermute_b32 v69, v85, v68
	s_waitcnt lgkmcnt(0)
	v_add_f32_e32 v68, v68, v69
	v_fmamk_f32 v69, v68, 0x3a800000, v86
	v_mul_f32_e32 v68, 0x4b800000, v69
	v_cmp_gt_f32_e32 vcc, 0x800000, v69
	s_nop 1
	v_cndmask_b32_e32 v68, v69, v68, vcc
	v_rsq_f32_e32 v68, v68
	s_nop 0
	v_mul_f32_e32 v70, 0x45800000, v68
	v_cndmask_b32_e32 v68, v68, v70, vcc
	v_add_u32_e32 v96, 0x800, v92
	v_mov_b32_e32 v97, 0
	v_mul_f32_e32 v69, v69, v68
	v_lshl_add_u64 v[98:99], v[96:97], 2, s[100:101]
	s_mov_b64 exec, 1
	global_store_dword v[98:99], v69, off
	s_mov_b64 exec, -1
	v_lshlrev_b64 v[98:99], 11, v[96:97]
	v_lshl_add_u64 v[98:99], v[90:91], 0, v[98:99]
	v_mul_f32_e32 v32, v32, v68
	v_mul_f32_e32 v33, v33, v68
	v_mul_f32_e32 v34, v34, v68
	v_mul_f32_e32 v35, v35, v68
	v_cvt_pk_bf16_f32 v32, v32, v33
	v_cvt_pk_bf16_f32 v33, v34, v35
	global_store_dwordx2 v[98:99], v[32:33], off
	v_mul_f32_e32 v36, v36, v68
	v_mul_f32_e32 v37, v37, v68
	v_mul_f32_e32 v38, v38, v68
	v_mul_f32_e32 v39, v39, v68
	v_cvt_pk_bf16_f32 v36, v36, v37
	v_cvt_pk_bf16_f32 v37, v38, v39
	global_store_dwordx2 v[98:99], v[36:37], off offset:512
	v_mul_f32_e32 v40, v40, v68
	v_mul_f32_e32 v41, v41, v68
	v_mul_f32_e32 v42, v42, v68
	v_mul_f32_e32 v43, v43, v68
	v_cvt_pk_bf16_f32 v40, v40, v41
	v_cvt_pk_bf16_f32 v41, v42, v43
	global_store_dwordx2 v[98:99], v[40:41], off offset:1024
	v_mul_f32_e32 v44, v44, v68
	v_mul_f32_e32 v45, v45, v68
	v_mul_f32_e32 v46, v46, v68
	v_mul_f32_e32 v47, v47, v68
	v_cvt_pk_bf16_f32 v44, v44, v45
	v_cvt_pk_bf16_f32 v45, v46, v47
	global_store_dwordx2 v[98:99], v[44:45], off offset:1536
	v_mul_f32_e32 v64, v49, v49
	v_mul_f32_e32 v65, v53, v53
	v_mul_f32_e32 v66, v57, v57
	v_mul_f32_e32 v67, v61, v61
	v_fmac_f32_e32 v64, v48, v48
	v_fmac_f32_e32 v65, v52, v52
	v_fmac_f32_e32 v66, v56, v56
	v_fmac_f32_e32 v67, v60, v60
	v_fmac_f32_e32 v64, v50, v50
	v_fmac_f32_e32 v65, v54, v54
	v_fmac_f32_e32 v66, v58, v58
	v_fmac_f32_e32 v67, v62, v62
	v_fmac_f32_e32 v64, v51, v51
	v_fmac_f32_e32 v65, v55, v55
	v_fmac_f32_e32 v66, v59, v59
	v_fmac_f32_e32 v67, v63, v63
	v_add_f32_e32 v68, v64, v65
	v_add_f32_e32 v68, v68, v66
	v_add_f32_e32 v68, v68, v67
	ds_bpermute_b32 v69, v80, v68
	s_waitcnt lgkmcnt(0)
; __device__ __forceinline__ unsigned cvt_pk_bf16(float lo, float hi) { unsigned r; asm volatile("v_cvt_pk_bf16_f32 %0, %1, %2" : "=v"(r) : "v"(lo), "v"(hi)); return r; }
; __device__ __forceinline__ void cvt_job(int& tbase, const float* __restrict__ src, int Nsrc, int K, bf16_t* __restrict__ dst, int ndst, int mode,
;                                         const float* __restrict__ gain, const float* __restrict__ up_f, const float* __restrict__ up_b, int bi, int nb) {
;     const int lane = threadIdx.x & 63, gw = bi * 8 + (threadIdx.x >> 6), nw = nb * 8;
;     const int nT = ndst >> 6, kT = K >> 6, ntile = nT * kT;
;     int t0 = (gw - tbase % nw + nw) % nw; tbase += ntile;
;     for (int t = t0; t < ntile; t += nw) {
;         const int n0 = (t % nT) << 6, k0 = (t / nT) << 6, n = n0 + lane;
; __device__ __forceinline__ void rows_prenorm(const float* __restrict__ x, bf16_t* __restrict__ XN, float* __restrict__ RN, int bi, int nb, int nrows) {
;     ...
;         for (int u = 0; u < 2; ++u) { const float* xp = x + (size_t)(row + u * nw) * DM + 4 * lane;
; #pragma unroll
;             for (int c = 0; c < 4; ++c) v[u][c] = *(const f32x4*)(xp + 256 * c); }
; #pragma unroll
;         for (int u = 0; u < 2; ++u) {
; #pragma unroll
;             for (int c = 0; c < 4; ++c) ss[u] += sq4(v[u][c]);
;             ss[u] = wave_sum(ss[u]); const float ms = ss[u] * (1.0f / DM) + EPS, ri = rsqrtf(ms);
;             if (lane == 0) RN[row + u * nw] = ms * ri;
;             bf16_t* op = XN + (size_t)(row + u * nw) * DM + 4 * lane;
; #pragma unroll
;             for (int c = 0; c < 4; ++c) { u32x2 w; w.x = cvt_pk_bf16(v[u][c][0] * ri, v[u][c][1] * ri); w.y = cvt_pk_bf16(v[u][c][2] * ri, v[u][c][3] * ri); *(u32x2*)(op + 256 * c) = w; } }
	v_add_f32_e32 v68, v68, v69
	ds_bpermute_b32 v69, v81, v68
	s_waitcnt lgkmcnt(0)
	v_add_f32_e32 v68, v68, v69
	ds_bpermute_b32 v69, v82, v68
	s_waitcnt lgkmcnt(0)
	v_add_f32_e32 v68, v68, v69
	ds_bpermute_b32 v69, v83, v68
	s_waitcnt lgkmcnt(0)
	v_add_f32_e32 v68, v68, v69
	ds_bpermute_b32 v69, v84, v68
	s_waitcnt lgkmcnt(0)
	v_add_f32_e32 v68, v68, v69
	ds_bpermute_b32 v69, v85, v68
	s_waitcnt lgkmcnt(0)
	v_add_f32_e32 v68, v68, v69
	v_fmamk_f32 v69, v68, 0x3a800000, v86
	v_mul_f32_e32 v68, 0x4b800000, v69
	v_cmp_gt_f32_e32 vcc, 0x800000, v69
	s_nop 1
	v_cndmask_b32_e32 v68, v69, v68, vcc
	v_rsq_f32_e32 v68, v68
	s_nop 0
	v_mul_f32_e32 v70, 0x45800000, v68
	v_cndmask_b32_e32 v68, v68, v70, vcc
	v_add_u32_e32 v96, 0xc00, v92
	v_mov_b32_e32 v97, 0
	v_mul_f32_e32 v69, v69, v68
	v_lshl_add_u64 v[98:99], v[96:97], 2, s[100:101]
	s_mov_b64 exec, 1
	global_store_dword v[98:99], v69, off
	s_mov_b64 exec, -1
	v_lshlrev_b64 v[98:99], 11, v[96:97]
	v_lshl_add_u64 v[98:99], v[90:91], 0, v[98:99]
	v_mul_f32_e32 v48, v48, v68
	v_mul_f32_e32 v49, v49, v68
	v_mul_f32_e32 v50, v50, v68
	v_mul_f32_e32 v51, v51, v68
	v_cvt_pk_bf16_f32 v48, v48, v49
	v_cvt_pk_bf16_f32 v49, v50, v51
	global_store_dwordx2 v[98:99], v[48:49], off
	v_mul_f32_e32 v52, v52, v68
	v_mul_f32_e32 v53, v53, v68
	v_mul_f32_e32 v54, v54, v68
	v_mul_f32_e32 v55, v55, v68
	v_cvt_pk_bf16_f32 v52, v52, v53
	v_cvt_pk_bf16_f32 v53, v54, v55
	global_store_dwordx2 v[98:99], v[52:53], off offset:512
	v_mul_f32_e32 v56, v56, v68
	v_mul_f32_e32 v57, v57, v68
	v_mul_f32_e32 v58, v58, v68
	v_mul_f32_e32 v59, v59, v68
	v_cvt_pk_bf16_f32 v56, v56, v57
	v_cvt_pk_bf16_f32 v57, v58, v59
	global_store_dwordx2 v[98:99], v[56:57], off offset:1024
	v_mul_f32_e32 v60, v60, v68
	v_mul_f32_e32 v61, v61, v68
	v_mul_f32_e32 v62, v62, v68
	v_mul_f32_e32 v63, v63, v68
	v_cvt_pk_bf16_f32 v60, v60, v61
	v_cvt_pk_bf16_f32 v61, v62, v63
	global_store_dwordx2 v[98:99], v[60:61], off offset:1536
	v_add_u32_e32 v92, 0x1000, v92
	s_add_i32 s32, s32, -1
	s_cmp_lg_u32 s32, 0
	s_cbranch_scc1 .Lg1pn_loop
	s_lshl_b32 s28, s33, 3
	s_abs_i32 s29, s28
	v_cvt_f32_u32_e32 v0, s29
	s_mov_b32 s2, s93
	s_lshr_b32 s3, s2, 1
	v_rcp_iflag_f32_e32 v0, v0
	s_and_b32 s3, s3, 0x1ffffffc
	s_and_b32 s2, s2, 3
	s_or_b32 s2, s3, s2
	v_mul_f32_e32 v0, 0x4f7ffffe, v0
	v_cvt_u32_f32_e32 v0, v0
	s_lshl_b32 s2, s2, 3
	s_add_i32 s2, s2, s28
	s_waitcnt vmcnt(33)
	v_add_u32_e32 v46, s2, v177
	s_sub_i32 s2, 0, s29
	v_readfirstlane_b32 s30, v0
	s_mul_i32 s2, s2, s30
	v_sub_u32_e32 v2, 0, v46
	s_mul_hi_u32 s2, s30, s2
	v_max_i32_e32 v2, v46, v2
	s_add_i32 s30, s30, s2
	v_mul_hi_u32 v0, v2, s30
	v_mul_lo_u32 v0, v0, s29
	v_sub_u32_e32 v0, v2, v0
	v_subrev_u32_e32 v2, s29, v0
	v_cmp_le_u32_e32 vcc, s29, v0
	v_ashrrev_i32_e32 v1, 31, v46
	s_movk_i32 s2, 0x2c0
	v_cndmask_b32_e32 v0, v0, v2, vcc
	v_subrev_u32_e32 v2, s29, v0
	v_cmp_le_u32_e32 vcc, s29, v0
	s_nop 1
	v_cndmask_b32_e32 v0, v0, v2, vcc
	v_xor_b32_e32 v0, v0, v1
	v_sub_u32_e32 v10, v0, v1
	v_cmp_gt_i32_e32 vcc, s2, v10
	s_and_saveexec_b64 s[2:3], vcc
	s_cbranch_execz .LBB0_92
	v_lshl_or_b32 v11, v10, 6, v165
	s_lshl_b32 s24, s28, 6
	s_mov_b64 s[4:5], 0
	v_mov_b64_e32 v[0:1], s[20:21]
	s_mov_b32 s25, 0x1e000
	s_mov_b32 s26, 0x20000
	s_mov_b32 s27, 0x22000
	s_mov_b32 s31, 0x24000
	s_mov_b32 s34, 0x26000
	s_mov_b32 s35, 0x28000
	s_mov_b32 s36, 0x2a000
	s_mov_b32 s37, 0x2c000
	s_mov_b32 s38, 0x2e000
	s_mov_b32 s39, 0x30000
	s_mov_b32 s40, 0x32000
	s_mov_b32 s41, 0x34000
	s_mov_b32 s42, 0x36000
	s_mov_b32 s43, 0x38000
	s_mov_b32 s44, 0x3a000
	s_mov_b32 s45, 0x3c000
	s_mov_b32 s46, 0x3f000
	s_mov_b32 s47, 0x3e000
	s_movk_i32 s48, 0x2bf
